# C: ki+gather2+epi + junk prefetch of K/V tile j+2 in NSA sel and window loops
# baseline (speedup 1.0000x reference)
; __device__ __forceinline__ void nsa_unit(Frame& F, int b, int g, int i, const bf16* QN, const bf16* KV, const bf16* KCMP, const float* GN, bf16* ON, int& itc) {
;     ...
;         for (int r = 0; r < 16; ++r) { oc0[r] = g0 * o0[r]; oc1[r] = g0 * o1[r]; }
;     }
;     __syncthreads();
;     {
;         LAS const float* impb = (LAS const float*)(lds + NS_IMP);
;         LAS u64* maskl = (LAS u64*)(lds + NS_MASK);
; #pragma unroll 1
;         for (int q = 0; q < 8; ++q) {
;             const int tok = F.wave * 8 + q, j = lane;
;             const float v = ((impb[(0 * 64 + tok) * 64 + j] + impb[(1 * 64 + tok) * 64 + j]) + impb[(2 * 64 + tok) * 64 + j]) + impb[(3 * 64 + tok) * 64 + j];
;             const bool vis = j <= i, forced = vis && ((j == 0) | (j == i) | (j == i - 1)), cand = vis && !forced;
;             const int k = 16 - __builtin_popcountll(__ballot(forced)), ncand = __builtin_popcountll(__ballot(cand));
;             const float vc = cand ? v : -INFINITY;
;             u64 msk;
;             if (ncand <= k) msk = __ballot(vis);
;             else {
;                 float lo = 0.f, hi = 8.f, thr = 0.f;
;                 for (int itn = 0; itn < 64; ++itn) {
;                     const float mid = 0.5f * (lo + hi);
;                     if (!(mid > lo && mid < hi)) { thr = lo; break; }
;                     const int c = __builtin_popcountll(__ballot(vc >= mid));
;                     if (c == k) { thr = mid; break; }
;                     if (c > k) lo = mid; else hi = mid;
;                     thr = lo;
;                 }
;                 const int need = k - __builtin_popcountll(__ballot(vc > thr));
;                 const bool eq = vc == thr; const u64 meq = __ballot(eq);
;                 msk = __ballot(forced || (vc > thr) || (eq && mbcnt64(meq) < need));
;             }
;             if (lane == 0) maskl[tok] = msk;
;         }
;     }
;     __syncthreads();
;     const u64 mymask = ((LAS const u64*)(lds + NS_MASK))[32 * th + r32];
; #pragma unroll
;     for (int r = 0; r < 16; ++r) { accl[r * 64] = oc0[r]; accl[(16 + r) * 64] = oc1[r]; }
;     {
;         NsaSm ss{-1e30f, 0.f}; f32x16 o0, o1;
; #pragma unroll
;         for (int r = 0; r < 16; ++r) { o0[r] = 0.f; o1[r] = 0.f; }
;         Ks = launder(KV) + ((size_t)(2 * NB * 4 + bg) * SEQ) * 64; Vs = Ks + ((size_t)NB * 4 * SEQ) * 64;
;         NSA_LOAD(Ks, Vs, 0);
.LBB0_921:
	v_mul_f32_e32 v0, v104, v32
	v_mul_f32_e32 v3, v104, v33
	s_mov_b64 s[0:1], s[8:9]
	v_readlane_b32 s14, v253, 25
	v_mul_f32_e32 v2, v104, v16
	v_mul_f32_e32 v4, v104, v17
	v_mul_f32_e32 v5, v104, v34
	v_mul_f32_e32 v6, v104, v18
	v_mul_f32_e32 v7, v104, v35
	v_mul_f32_e32 v8, v104, v19
	v_mul_f32_e32 v9, v104, v36
	v_mul_f32_e32 v10, v104, v20
	v_mul_f32_e32 v11, v104, v37
	v_mul_f32_e32 v12, v104, v21
	v_mul_f32_e32 v13, v104, v38
	v_mul_f32_e32 v14, v104, v22
	v_mul_f32_e32 v15, v104, v39
	v_mul_f32_e32 v16, v104, v23
	v_mul_f32_e32 v17, v104, v40
	v_mul_f32_e32 v18, v104, v24
	v_mul_f32_e32 v19, v104, v41
	v_mul_f32_e32 v20, v104, v25
	v_mul_f32_e32 v21, v104, v42
	v_mul_f32_e32 v22, v104, v26
	v_mul_f32_e32 v23, v104, v43
	v_mul_f32_e32 v24, v104, v27
	v_mul_f32_e32 v25, v104, v44
	v_mul_f32_e32 v26, v104, v28
	v_mul_f32_e32 v27, v104, v45
	v_mul_f32_e32 v28, v104, v29
	v_mul_f32_e32 v29, v104, v46
	v_mul_f32_e32 v32, v104, v30
	v_mul_f32_e32 v33, v104, v47
	v_mul_f32_e32 v34, v104, v31
	s_waitcnt lgkmcnt(0)
	s_barrier
	ds_read_b64 v[30:31], v131
	ds_write2st64_b32 v130, v0, v3 offset0:128 offset1:129
	ds_write2st64_b32 v130, v2, v4 offset0:144 offset1:145
	ds_write2st64_b32 v130, v5, v7 offset0:130 offset1:131
	ds_write2st64_b32 v130, v6, v8 offset0:146 offset1:147
	ds_write2st64_b32 v130, v9, v11 offset0:132 offset1:133
	ds_write2st64_b32 v130, v10, v12 offset0:148 offset1:149
	ds_write2st64_b32 v130, v13, v15 offset0:134 offset1:135
	ds_write2st64_b32 v130, v14, v16 offset0:150 offset1:151
	ds_write2st64_b32 v130, v17, v19 offset0:136 offset1:137
	ds_write2st64_b32 v130, v18, v20 offset0:152 offset1:153
	ds_write2st64_b32 v130, v21, v23 offset0:138 offset1:139
	ds_write2st64_b32 v130, v22, v24 offset0:154 offset1:155
	ds_write2st64_b32 v130, v25, v27 offset0:140 offset1:141
	ds_write2st64_b32 v130, v26, v28 offset0:156 offset1:157
	ds_write2st64_b32 v130, v29, v33 offset0:142 offset1:143
	ds_write2st64_b32 v130, v32, v34 offset0:158 offset1:159
	v_readlane_b32 s15, v253, 26
	s_add_u32 s14, s0, s14
	s_addc_u32 s15, s1, s15
	v_lshl_add_u64 v[2:3], s[14:15], 0, v[110:111]
	v_add_co_u32_e32 v4, vcc, s64, v2
	v_mov_b32_e32 v14, v1
	s_nop 0
	v_addc_co_u32_e32 v5, vcc, 0, v3, vcc
	global_load_dwordx4 v[18:21], v[2:3], off
	global_load_dwordx4 v[22:25], v[4:5], off
	s_mov_b64 s[100:101], 0x2000
	v_lshl_add_u64 v[214:215], v[2:3], 0, s[100:101]
	v_lshl_add_u64 v[212:213], v[4:5], 0, s[100:101]
	global_load_dwordx4 v[216:219], v[214:215], off
	global_load_dwordx4 v[220:223], v[212:213], off
	v_mov_b32_e32 v15, v1
	s_add_i32 s22, s48, 0xffffff50
	s_lshl_b32 s33, s49, 13
	v_mov_b32_e32 v0, v1
	v_mov_b32_e32 v2, v1
	v_mov_b32_e32 v3, v1
	v_mov_b32_e32 v4, v1
	v_mov_b32_e32 v5, v1
	v_mov_b32_e32 v6, v1
	v_mov_b32_e32 v7, v1
	v_mov_b32_e32 v8, v1
	v_mov_b32_e32 v9, v1
	v_mov_b32_e32 v10, v1
	v_mov_b32_e32 v11, v1
	v_mov_b32_e32 v12, v1
	v_mov_b32_e32 v13, v1
	v_mov_b64_e32 v[46:47], v[14:15]
	s_add_u32 s0, s0, s57
	v_mov_b64_e32 v[44:45], v[12:13]
	v_mov_b64_e32 v[42:43], v[10:11]
	v_mov_b64_e32 v[40:41], v[8:9]
	v_mov_b64_e32 v[38:39], v[6:7]
	v_mov_b64_e32 v[36:37], v[4:5]
	v_mov_b64_e32 v[34:35], v[2:3]
	v_mov_b64_e32 v[32:33], v[0:1]
	v_mov_b64_e32 v[16:17], v[14:15]
	s_mov_b32 s17, 0
	s_addc_u32 s1, s1, s58
	s_add_u32 s44, s36, 1
	s_waitcnt vmcnt(5)
	v_add_u32_e32 v96, s37, v134
	s_add_i32 s16, s33, 0x2000
	v_mov_b32_e32 v97, 0
	v_mov_b32_e32 v99, 0xf149f2ca
	s_mov_b64 s[14:15], 0
	v_mov_b64_e32 v[14:15], v[12:13]
	v_mov_b64_e32 v[12:13], v[10:11]
	v_mov_b64_e32 v[10:11], v[8:9]
	v_mov_b64_e32 v[8:9], v[6:7]
	v_mov_b64_e32 v[6:7], v[4:5]
	v_mov_b64_e32 v[4:5], v[2:3]
	v_mov_b64_e32 v[2:3], v[0:1]
.LBB0_922:
	s_and_b32 s26, s33, 0x2000
	v_add_u32_e32 v0, s26, v120
	s_waitcnt vmcnt(3)
	ds_write_b128 v0, v[18:21]
	v_add_u32_e32 v0, s26, v121
	s_cmp_ge_u32 s14, s36
	s_waitcnt vmcnt(2)
	ds_write_b128 v0, v[22:25] offset:16384
	s_cbranch_scc1 .LBB0_924
	v_lshl_add_u64 v[22:23], s[0:1], 0, v[110:111]
	v_add_co_u32_e32 v18, vcc, 0xff800000, v22
	s_nop 1
	v_addc_co_u32_e32 v19, vcc, -1, v23, vcc
	v_lshl_add_u64 v[212:213], v[22:23], 0, s[100:101]
	v_add_co_u32_e32 v214, vcc, 0xff800000, v212
	s_nop 1
	v_addc_co_u32_e32 v215, vcc, -1, v213, vcc
	global_load_dwordx4 v[18:21], v[18:19], off
	s_nop 0
	global_load_dwordx4 v[22:25], v[22:23], off
	global_load_dwordx4 v[216:219], v[214:215], off
	global_load_dwordx4 v[220:223], v[212:213], off

; template <class T> __device__ __forceinline__ T* launder(T* p) { asm volatile("" : "+s"(p)); return p; }
; __device__ __forceinline__ float xsum32(float v) { const SwapPair r = swap32(v); return __builtin_bit_cast(float, r.a) + __builtin_bit_cast(float, r.b); }
; #define NSA_LOAD(Kp, Vp, jb) do { kr = *(const GAS v4u*)((const GAS char*)((Kp) + (size_t)(jb) * 4096) + toff); vr = *(const GAS v4u*)((const GAS char*)((Vp) + (size_t)(jb) * 4096) + toff); } while (0)
; #define NSA_STAGE() do { nsa_stage_store(lds, itc & 1, tid, kr, vr); } while (0)
; __device__ __forceinline__ void nsa_unit(Frame& F, int b, int g, int i, const bf16* QN, const bf16* KV, const bf16* KCMP, const float* GN, bf16* ON, int& itc) {
;     ...
;         const float lt = xsum32(ss.l), f = lt > 0.f ? g1 / lt : 0.f;
; #pragma unroll
;         for (int r = 0; r < 16; ++r) { accl[r * 64] += f * o0[r]; accl[(16 + r) * 64] += f * o1[r]; }
;     }
;     {
;         NsaSm sw{-1e30f, 0.f}; f32x16 o0, o1;
; #pragma unroll
;         for (int r = 0; r < 16; ++r) { o0[r] = 0.f; o1[r] = 0.f; }
;     ...
;         const int j0 = 0;
;     ...
;         const int j0 = max(i - 8, 0);
;     ...
;         Kw = launder(KV) + ((size_t)(4 * NB * 4 + bg) * SEQ) * 64; Vw = Kw + ((size_t)NB * 4 * SEQ) * 64;
;         NSA_LOAD(Kw, Vw, j0);
;     ...
;         for (int jb = j0; jb <= i; ++jb) {
;             NSA_STAGE(); if (jb < i) NSA_LOAD(Kw, Vw, jb + 1);
.LBB0_931:
	v_mov_b32_e32 v0, v52
	s_add_i32 s17, s49, s14
	s_nop 0
	v_permlane32_swap_b32_e32 v52, v0
	v_add_f32_e32 v0, v52, v0
	s_waitcnt vmcnt(1)
	v_div_scale_f32 v18, s[0:1], v0, v0, v105
	v_rcp_f32_e32 v19, v18
	v_cmp_lt_f32_e64 s[42:43], 0, v0
	s_max_i32 s14, s36, 8
	s_add_i32 s22, s14, -8
	v_fma_f32 v20, -v18, v19, 1.0
	v_fmac_f32_e32 v19, v20, v19
	v_div_scale_f32 v20, vcc, v105, v0, v105
	v_mul_f32_e32 v21, v20, v19
	s_waitcnt vmcnt(0)
	v_fma_f32 v22, -v18, v21, v20
	v_fmac_f32_e32 v21, v22, v19
	v_fma_f32 v18, -v18, v21, v20
	v_div_fmas_f32 v18, v18, v19, v21
	v_div_fixup_f32 v0, v18, v0, v105
	ds_read2st64_b32 v[18:19], v130 offset0:128 offset1:129
	ds_read2st64_b32 v[20:21], v130 offset0:144 offset1:145
	v_cndmask_b32_e64 v0, 0, v0, s[42:43]
	v_mov_b32_e32 v31, 0
	s_mov_b64 s[0:1], s[8:9]
	s_waitcnt lgkmcnt(1)
	v_fma_f32 v2, v2, v0, v18
	s_waitcnt lgkmcnt(0)
	v_fma_f32 v18, v32, v0, v20
	v_fmac_f32_e32 v19, v3, v0
	v_fmac_f32_e32 v21, v33, v0
	ds_write2st64_b32 v130, v2, v19 offset0:128 offset1:129
	ds_write2st64_b32 v130, v18, v21 offset0:144 offset1:145
	ds_read2st64_b32 v[2:3], v130 offset0:130 offset1:131
	ds_read2st64_b32 v[18:19], v130 offset0:146 offset1:147
	s_cmp_le_i32 s22, s36
	s_waitcnt lgkmcnt(1)
	v_fma_f32 v2, v4, v0, v2
	s_waitcnt lgkmcnt(0)
	v_fma_f32 v4, v34, v0, v18
	v_fmac_f32_e32 v3, v5, v0
	v_fmac_f32_e32 v19, v35, v0
	ds_write2st64_b32 v130, v2, v3 offset0:130 offset1:131
	ds_write2st64_b32 v130, v4, v19 offset0:146 offset1:147
	ds_read2st64_b32 v[2:3], v130 offset0:132 offset1:133
	ds_read2st64_b32 v[4:5], v130 offset0:148 offset1:149
	s_waitcnt lgkmcnt(1)
	v_fma_f32 v2, v6, v0, v2
	s_waitcnt lgkmcnt(0)
	v_fma_f32 v4, v36, v0, v4
	v_fmac_f32_e32 v3, v7, v0
	v_fmac_f32_e32 v5, v37, v0
	ds_write2st64_b32 v130, v2, v3 offset0:132 offset1:133
	ds_write2st64_b32 v130, v4, v5 offset0:148 offset1:149
	ds_read2st64_b32 v[2:3], v130 offset0:134 offset1:135
	ds_read2st64_b32 v[4:5], v130 offset0:150 offset1:151
	s_waitcnt lgkmcnt(1)
	v_fma_f32 v2, v8, v0, v2
	s_waitcnt lgkmcnt(0)
	v_fma_f32 v4, v38, v0, v4
	v_fmac_f32_e32 v3, v9, v0
	v_fmac_f32_e32 v5, v39, v0
	ds_write2st64_b32 v130, v2, v3 offset0:134 offset1:135
	ds_write2st64_b32 v130, v4, v5 offset0:150 offset1:151
	ds_read2st64_b32 v[2:3], v130 offset0:136 offset1:137
	ds_read2st64_b32 v[4:5], v130 offset0:152 offset1:153
	s_waitcnt lgkmcnt(1)
	v_fma_f32 v2, v10, v0, v2
	s_waitcnt lgkmcnt(0)
	v_fma_f32 v4, v40, v0, v4
	v_fmac_f32_e32 v3, v11, v0
	v_fmac_f32_e32 v5, v41, v0
	ds_write2st64_b32 v130, v2, v3 offset0:136 offset1:137
	ds_write2st64_b32 v130, v4, v5 offset0:152 offset1:153
	ds_read2st64_b32 v[2:3], v130 offset0:138 offset1:139
	ds_read2st64_b32 v[4:5], v130 offset0:154 offset1:155
	s_waitcnt lgkmcnt(1)
	v_fma_f32 v2, v12, v0, v2
	s_waitcnt lgkmcnt(0)
	v_fma_f32 v4, v42, v0, v4
	v_fmac_f32_e32 v3, v13, v0
	v_fmac_f32_e32 v5, v43, v0
	ds_write2st64_b32 v130, v2, v3 offset0:138 offset1:139
	ds_write2st64_b32 v130, v4, v5 offset0:154 offset1:155
	ds_read2st64_b32 v[2:3], v130 offset0:140 offset1:141
	ds_read2st64_b32 v[4:5], v130 offset0:156 offset1:157
	s_waitcnt lgkmcnt(1)
	v_fma_f32 v2, v14, v0, v2
	s_waitcnt lgkmcnt(0)
	v_fma_f32 v4, v44, v0, v4
	v_fmac_f32_e32 v3, v15, v0
	v_fmac_f32_e32 v5, v45, v0
	ds_write2st64_b32 v130, v2, v3 offset0:140 offset1:141
	ds_write2st64_b32 v130, v4, v5 offset0:156 offset1:157
	ds_read2st64_b32 v[2:3], v130 offset0:142 offset1:143
	ds_read2st64_b32 v[4:5], v130 offset0:158 offset1:159
	s_waitcnt lgkmcnt(1)
	v_fma_f32 v2, v16, v0, v2
	s_waitcnt lgkmcnt(0)
	v_fma_f32 v4, v46, v0, v4
	v_fmac_f32_e32 v3, v17, v0
	v_fmac_f32_e32 v5, v47, v0
	ds_write2st64_b32 v130, v2, v3 offset0:142 offset1:143
	ds_write2st64_b32 v130, v4, v5 offset0:158 offset1:159
	s_cbranch_scc0 .LBB0_884
	v_readlane_b32 s34, v254, 31
	v_readlane_b32 s35, v254, 32
	s_add_u32 s15, s0, s34
	s_addc_u32 s33, s1, s35
	s_lshl_b64 s[26:27], s[22:23], 13
	s_add_u32 s26, s15, s26
	s_addc_u32 s27, s33, s27
	v_lshl_add_u64 v[2:3], s[26:27], 0, v[110:111]
	v_add_co_u32_e32 v4, vcc, s64, v2
	s_addk_i32 s48, 0xff51
	s_nop 0
	v_addc_co_u32_e32 v5, vcc, 0, v3, vcc
	global_load_dwordx4 v[100:103], v[4:5], off
	global_load_dwordx4 v[96:99], v[2:3], off
	v_lshl_add_u64 v[214:215], v[2:3], 0, s[100:101]
	v_lshl_add_u64 v[212:213], v[4:5], 0, s[100:101]
	global_load_dwordx4 v[216:219], v[214:215], off
	global_load_dwordx4 v[220:223], v[212:213], off
	s_add_u32 s0, s0, s34
	s_addc_u32 s1, s1, s35
	s_lshl_b32 s15, s14, 13
	s_add_i32 s15, s15, 0xffff2000
	s_add_u32 s0, s0, s15
	v_mov_b32_e32 v14, v1
	v_mov_b32_e32 v15, v1
	s_addc_u32 s1, s1, 0
	s_add_i32 s15, s25, s37
	s_lshl_b32 s26, s14, 6
	v_mov_b32_e32 v0, v1
	v_mov_b32_e32 v2, v1
	v_mov_b32_e32 v3, v1
	v_mov_b32_e32 v4, v1
	v_mov_b32_e32 v5, v1
	v_mov_b32_e32 v6, v1
	v_mov_b32_e32 v7, v1
	v_mov_b32_e32 v8, v1
	v_mov_b32_e32 v9, v1
	v_mov_b32_e32 v10, v1
	v_mov_b32_e32 v11, v1
	v_mov_b32_e32 v12, v1
	v_mov_b32_e32 v13, v1
	v_mov_b64_e32 v[30:31], v[14:15]
	v_mov_b64_e32 v[46:47], v[14:15]
	s_sub_i32 s22, s15, s26
	s_add_i32 s33, s26, 0xfffffe00
	s_add_i32 s37, s14, -9
	v_mov_b32_e32 v104, 0
	v_mov_b32_e32 v105, 0xf149f2ca
	v_mov_b64_e32 v[28:29], v[12:13]
	v_mov_b64_e32 v[26:27], v[10:11]
	v_mov_b64_e32 v[24:25], v[8:9]
	v_mov_b64_e32 v[22:23], v[6:7]
	v_mov_b64_e32 v[20:21], v[4:5]
	v_mov_b64_e32 v[18:19], v[2:3]
	v_mov_b64_e32 v[16:17], v[0:1]
	v_mov_b64_e32 v[44:45], v[12:13]
	v_mov_b64_e32 v[42:43], v[10:11]
	v_mov_b64_e32 v[40:41], v[8:9]
	v_mov_b64_e32 v[38:39], v[6:7]
	v_mov_b64_e32 v[36:37], v[4:5]
	v_mov_b64_e32 v[34:35], v[2:3]
	v_mov_b64_e32 v[32:33], v[0:1]
.LBB0_933:
	s_add_i32 s37, s37, 1
	s_and_b32 s26, s16, 0x2000
	s_cmp_ge_u32 s37, s36
	v_add_u32_e32 v0, s26, v120
	s_cselect_b64 s[14:15], -1, 0
	s_waitcnt vmcnt(2)
	ds_write_b128 v0, v[96:99]
	v_add_u32_e32 v0, s26, v121
	s_and_b64 vcc, exec, s[14:15]
	ds_write_b128 v0, v[100:103] offset:16384
	s_cbranch_vccnz .LBB0_935
	v_lshl_add_u64 v[2:3], s[0:1], 0, v[110:111]
	v_add_co_u32_e32 v4, vcc, 0x800000, v2
	s_nop 1
	v_addc_co_u32_e32 v5, vcc, 0, v3, vcc
	global_load_dwordx4 v[96:99], v[2:3], off
	global_load_dwordx4 v[100:103], v[4:5], off
	v_lshl_add_u64 v[214:215], v[2:3], 0, s[100:101]
	v_lshl_add_u64 v[212:213], v[4:5], 0, s[100:101]
	global_load_dwordx4 v[216:219], v[214:215], off
	global_load_dwordx4 v[220:223], v[212:213], off
